# P2 phase-start parameter loads also issued during the preceding grid barrier wait
# speedup vs baseline: 1.0008x; 1.0008x over previous
.Lgb1_poll:
	s_or_b64 exec, exec, s[0:1]
	v_mov_b32_e32 v32, 0x3308000
	v_mov_b32_e32 v33, 0x3308068
	global_load_dwordx2 v[34:35], v32, s[44:45] offset:128
	global_load_dwordx2 v[36:37], v33, s[44:45]
	s_and_b64 exec, s[0:1], s[10:11]
	v_mov_b32_e32 v1, 0x3323000
	s_mov_b32 s77, 0

.Lgb1_other:
	s_or_b64 exec, exec, s[0:1]
	v_mov_b32_e32 v32, 0x3308000
	v_mov_b32_e32 v33, 0x3308068
	global_load_dwordx2 v[34:35], v32, s[44:45] offset:128
	global_load_dwordx2 v[36:37], v33, s[44:45]
.LBB0_285:
	s_or_b64 exec, exec, s[0:1]
	v_mov_b32_e32 v2, 0x3308000
	s_waitcnt lgkmcnt(0)
	s_barrier
	v_mov_b32_e32 v0, s44
	v_mov_b32_e32 v1, s45
	s_waitcnt vmcnt(0)
	v_mov_b32_e32 v48, v34
	v_mov_b32_e32 v49, v35
	s_add_u32 s6, s44, 0x3308068
	s_addc_u32 s7, s45, 0
	s_add_u32 s56, s44, 0x33080d0
	s_addc_u32 s57, s45, 0
	s_cmpk_lt_i32 s52, 0x1000
	s_cselect_b64 s[58:59], -1, 0
	s_cmpk_gt_i32 s52, 0xfff
	s_waitcnt vmcnt(1)
	v_readfirstlane_b32 s4, v0
	v_readfirstlane_b32 s5, v1
	s_cbranch_scc1 .LBB0_312
	v_mov_b32_e32 v51, 0
	v_mov_b32_e32 v0, v36
	v_mov_b32_e32 v1, v37
	s_add_u32 s8, s4, 0x3400000
	s_addc_u32 s9, s5, 0
	s_add_u32 s14, s4, 0x9000000
	s_addc_u32 s15, s5, 0
	s_add_u32 s16, s4, 0xa800000
	s_addc_u32 s17, s5, 0
	s_add_u32 s29, s4, 0x1b800000
	v_lshlrev_b32_e32 v50, 4, v176
	v_mbcnt_hi_u32_b32 v5, -1, v228
	s_addc_u32 s30, s5, 0
	s_mov_b64 s[2:3], 0xd000000
	v_lshlrev_b32_e32 v4, 4, v173
	v_lshl_add_u64 v[2:3], s[4:5], 0, v[50:51]
	v_and_b32_e32 v6, 64, v5
	s_add_u32 s31, s4, 0x1c400000
	v_and_b32_e32 v70, 48, v4
	v_xor_b32_e32 v4, 4, v5
	v_lshl_add_u64 v[54:55], v[2:3], 0, s[2:3]
	v_add_u32_e32 v2, 64, v6
	s_addc_u32 s33, s5, 0
	s_lshl_b32 s2, s18, 6
	s_lshl_b32 s3, s85, 3
	v_cmp_lt_i32_e32 vcc, v4, v2
	s_add_i32 s3, s3, s2
	v_lshlrev_b32_e32 v50, 5, v176
	v_cndmask_b32_e32 v2, v5, v4, vcc
	v_or_b32_e32 v72, s3, v174
	v_lshlrev_b32_e32 v52, 3, v176
	v_cmp_gt_u32_e64 s[0:1], 4, v176
	v_lshlrev_b32_e32 v53, 8, v176
	s_movk_i32 s24, 0x1200
	s_movk_i32 s25, 0xff
	s_mov_b32 s26, 0xffff0000
	v_mov_b32_e32 v68, 0x358637bd
	s_mov_b32 s27, 0xf800000
	v_mov_b32_e32 v69, 0x260
	s_movk_i32 s28, 0x7fff
	v_lshlrev_b32_e32 v71, 2, v2
	s_lshl_b32 s34, s46, 12
	s_lshl_b32 s35, s46, 6
	v_lshlrev_b32_e32 v73, 6, v72
	s_mov_b32 s36, s52
	s_waitcnt vmcnt(0)
	v_lshl_add_u64 v[56:57], v[0:1], 0, v[50:51]
	s_branch .LBB0_288
